# DA attention loop hand-rewritten too: conflict-free V^T LDS layout with b64 accesses and LDS fragment prefetch (MLA loop as before)
# speedup vs baseline: 1.0257x; 1.0257x over previous
; DI U4 pack8(const float (&x)[8]) { return mku4(pack2(x[0], x[1]), pack2(x[2], x[3]), pack2(x[4], x[5]), pack2(x[6], x[7])); }
; DI f32x16 zero16() { f32x16 z; for (int i = 0; i < 16; ++i) z[i] = 0.f; return z; }
;     ...
;       const int it2 = item - n_mla;
;       const int b = it2 / 528, rem = it2 % 528, qb = rem >> 2, hd = rem & 3;
;       const int nk = qb < 4 ? CTX : TT;
;       constexpr int KL = 136;
;       u16* Ks = (u16*)ldsb; u16* Vs = Ks + 64 * KL;
;       const int comp = w >> 1;
;       const int tq = qb * 64 + (w & 1) * 32 + r; const size_t qrow = (size_t)b * TT + tq;
;       bf16x8 q[4];
;       {
;         const float sc = 0.125f * L2E;
; #pragma unroll
;         for (int ks = 0; ks < 4; ++ks) { U4 v = *(const U4*)(daq + qrow * 512 + hd * 128 + comp * 64 + ks * 16 + h * 8); float tmp[8]; unpack8(v, tmp);
; #pragma unroll
;           for (int j = 0; j < 8; ++j) tmp[j] *= sc;
;           q[ks] = __builtin_bit_cast(bf16x8, pack8(tmp)); }
;       }
;       AttnState<64> st; for (int eb = 0; eb < 4; ++eb) st.ot[eb] = zero16(); st.m = -1e30f; st.l = 0.f;
;       U4 rk[4], rv[4];
;       const u16* kbase = dak + ((size_t)b * TT) * 512 + hd * 128; const unsigned koff0 = (unsigned)((tid >> 4) * 512 + (tid & 15) * 8);
;       const u16* vbase = davt + ((size_t)b * 512 + hd * 128) * TT; const unsigned voff0 = (unsigned)((tid >> 3) * TT + (tid & 7) * 8);
;       auto gl = [&](int k0) {
; #pragma unroll
;         for (int i = 0; i < 4; ++i) rk[i] = *(const U4*)(kbase + (koff0 + (unsigned)((k0 + 16 * i) * 512)));
; #pragma unroll
;         for (int i = 0; i < 4; ++i) rv[i] = *(const U4*)(vbase + (voff0 + (unsigned)(32 * i * TT + k0)));
;       };
;       gl(0);
.LBB0_680:
	s_add_i32 s19, s18, 0xfffffbe0
	s_mul_hi_u32 s20, s19, 0x3e0f83e1
	s_lshr_b32 s44, s20, 7
	s_mul_i32 s20, s44, 0x210
	s_sub_i32 s19, s19, s20
	s_lshl_b32 s20, s19, 4
	s_and_b32 s42, s20, 0x3fc0
	s_lshl_b32 s20, s19, 7
	s_and_b32 s45, s20, 0x180
	v_or_b32_e32 v0, s42, v221
	v_mov_b32_e32 v2, 0x2100
	s_lshl_b32 s20, s45, 1
	v_mad_u64_u32 v[2:3], s[42:43], s44, v2, v[0:1]
	s_mul_i32 s43, s44, 0x840000
	s_cmp_lt_u32 s19, 16
	s_movk_i32 s19, 0x2100
	s_mul_hi_u32 s42, s44, 0x840000
	s_cselect_b32 s19, 0x100, s19
	s_add_u32 s43, s61, s43
	v_lshlrev_b64 v[2:3], 10, v[2:3]
	s_addc_u32 s52, s62, s42
	v_lshl_add_u64 v[2:3], s[10:11], 0, v[2:3]
	s_add_u32 s42, s43, s20
	v_lshl_add_u64 v[194:195], v[2:3], 0, s[20:21]
	s_addc_u32 s43, s52, 0
	s_lshl_b32 s20, s44, 9
	s_or_b32 s20, s20, s45
	v_lshl_add_u64 v[2:3], v[160:161], 1, v[194:195]
	v_mov_b32_e32 v193, v1
	s_mul_hi_u32 s45, s20, 0x4200
	s_mulk_i32 s20, 0x4200
	v_lshl_add_u64 v[14:15], v[2:3], 0, v[192:193]
	s_add_u32 s44, s63, s20
	global_load_dwordx4 v[2:5], v[14:15], off
	global_load_dwordx4 v[6:9], v[14:15], off offset:32
	global_load_dwordx4 v[10:13], v[14:15], off offset:64
	s_nop 0
	global_load_dwordx4 v[14:17], v[14:15], off offset:96
	v_lshl_add_u64 v[18:19], v[168:169], 1, s[42:43]
	s_addc_u32 s45, s64, s45
	v_lshl_add_u64 v[20:21], v[172:173], 1, s[42:43]
	v_lshl_add_u64 v[22:23], v[174:175], 1, s[42:43]
	v_lshl_add_u64 v[24:25], v[176:177], 1, s[42:43]
	global_load_dwordx4 v[112:115], v[18:19], off
	global_load_dwordx4 v[116:119], v[20:21], off
	global_load_dwordx4 v[120:123], v[22:23], off
	global_load_dwordx4 v[124:127], v[24:25], off
	v_lshl_add_u64 v[18:19], v[170:171], 1, s[44:45]
	v_lshl_add_u64 v[20:21], v[178:179], 1, s[44:45]
	v_lshl_add_u64 v[22:23], v[180:181], 1, s[44:45]
	v_lshl_add_u64 v[24:25], v[182:183], 1, s[44:45]
	global_load_dwordx4 v[128:131], v[18:19], off
	global_load_dwordx4 v[132:135], v[20:21], off
	global_load_dwordx4 v[144:147], v[22:23], off
	global_load_dwordx4 v[148:151], v[24:25], off
	s_mov_b32 s20, 0x3e38aa3b
	v_mov_b32_e32 v0, v1
	s_movk_i32 s52, 0x400
	s_mov_b32 s70, 0
	v_mov_b32_e32 v203, 0xf149f2ca
	v_mov_b32_e32 v193, 0
	v_mov_b32_e32 v196, v189
	s_waitcnt vmcnt(11)
	v_lshlrev_b32_e32 v18, 16, v2
	v_and_b32_e32 v19, 0xffff0000, v2
	v_lshlrev_b32_e32 v2, 16, v3
	v_and_b32_e32 v3, 0xffff0000, v3
	v_lshlrev_b32_e32 v20, 16, v4
	v_and_b32_e32 v21, 0xffff0000, v4
	v_lshlrev_b32_e32 v4, 16, v5
	v_and_b32_e32 v5, 0xffff0000, v5
	s_waitcnt vmcnt(10)
	v_lshlrev_b32_e32 v22, 16, v6
	v_and_b32_e32 v23, 0xffff0000, v6
	v_lshlrev_b32_e32 v6, 16, v7
	v_and_b32_e32 v7, 0xffff0000, v7
	v_lshlrev_b32_e32 v24, 16, v8
	v_and_b32_e32 v25, 0xffff0000, v8
	v_lshlrev_b32_e32 v8, 16, v9
	v_and_b32_e32 v9, 0xffff0000, v9
	v_pk_mul_f32 v[2:3], v[2:3], s[20:21] op_sel_hi:[1,0]
	v_pk_mul_f32 v[4:5], v[4:5], s[20:21] op_sel_hi:[1,0]
	v_pk_mul_f32 v[6:7], v[6:7], s[20:21] op_sel_hi:[1,0]
	v_pk_mul_f32 v[8:9], v[8:9], s[20:21] op_sel_hi:[1,0]
	s_waitcnt vmcnt(9)
	v_lshlrev_b32_e32 v26, 16, v10
	v_and_b32_e32 v27, 0xffff0000, v10
	v_lshlrev_b32_e32 v10, 16, v11
	v_and_b32_e32 v11, 0xffff0000, v11
	v_lshlrev_b32_e32 v28, 16, v12
	v_and_b32_e32 v29, 0xffff0000, v12
	v_lshlrev_b32_e32 v12, 16, v13
	v_and_b32_e32 v13, 0xffff0000, v13
	v_cvt_pk_bf16_f32 v137, v2, v3
	v_cvt_pk_bf16_f32 v139, v4, v5
	v_cvt_pk_bf16_f32 v141, v6, v7
	v_cvt_pk_bf16_f32 v143, v8, v9
	s_waitcnt vmcnt(8)
	v_lshlrev_b32_e32 v2, 16, v14
	v_and_b32_e32 v3, 0xffff0000, v14
	v_lshlrev_b32_e32 v4, 16, v15
	v_and_b32_e32 v5, 0xffff0000, v15
	v_lshlrev_b32_e32 v6, 16, v16
	v_and_b32_e32 v7, 0xffff0000, v16
	v_lshlrev_b32_e32 v8, 16, v17
	v_and_b32_e32 v9, 0xffff0000, v17
	v_pk_mul_f32 v[18:19], v[18:19], s[20:21] op_sel_hi:[1,0]
	v_pk_mul_f32 v[20:21], v[20:21], s[20:21] op_sel_hi:[1,0]
	v_pk_mul_f32 v[22:23], v[22:23], s[20:21] op_sel_hi:[1,0]
	v_pk_mul_f32 v[24:25], v[24:25], s[20:21] op_sel_hi:[1,0]
	v_pk_mul_f32 v[26:27], v[26:27], s[20:21] op_sel_hi:[1,0]
	v_pk_mul_f32 v[10:11], v[10:11], s[20:21] op_sel_hi:[1,0]
	v_pk_mul_f32 v[28:29], v[28:29], s[20:21] op_sel_hi:[1,0]
	v_pk_mul_f32 v[12:13], v[12:13], s[20:21] op_sel_hi:[1,0]
	v_pk_mul_f32 v[2:3], v[2:3], s[20:21] op_sel_hi:[1,0]
	v_pk_mul_f32 v[4:5], v[4:5], s[20:21] op_sel_hi:[1,0]
	v_pk_mul_f32 v[6:7], v[6:7], s[20:21] op_sel_hi:[1,0]
	v_pk_mul_f32 v[8:9], v[8:9], s[20:21] op_sel_hi:[1,0]
	v_mov_b32_e32 v14, v1
	v_mov_b32_e32 v15, v1
	v_cvt_pk_bf16_f32 v136, v18, v19
	v_cvt_pk_bf16_f32 v138, v20, v21
	v_cvt_pk_bf16_f32 v140, v22, v23
	v_cvt_pk_bf16_f32 v142, v24, v25
	v_cvt_pk_bf16_f32 v152, v26, v27
	v_cvt_pk_bf16_f32 v153, v10, v11
	v_cvt_pk_bf16_f32 v154, v28, v29
	v_cvt_pk_bf16_f32 v155, v12, v13
	v_cvt_pk_bf16_f32 v156, v2, v3
	v_cvt_pk_bf16_f32 v157, v4, v5
	v_cvt_pk_bf16_f32 v158, v6, v7
	v_cvt_pk_bf16_f32 v159, v8, v9
	v_mov_b32_e32 v2, v1
	v_mov_b32_e32 v3, v1
	v_mov_b32_e32 v4, v1
	v_mov_b32_e32 v5, v1
	v_mov_b32_e32 v6, v1
	v_mov_b32_e32 v7, v1
	v_mov_b32_e32 v8, v1
	v_mov_b32_e32 v9, v1
	v_mov_b32_e32 v10, v1
	v_mov_b32_e32 v11, v1
	v_mov_b32_e32 v12, v1
	v_mov_b32_e32 v13, v1
	v_mov_b64_e32 v[30:31], v[14:15]
	v_mov_b64_e32 v[46:47], v[14:15]
	v_mov_b64_e32 v[62:63], v[14:15]
	v_mov_b64_e32 v[78:79], v[14:15]
	v_mov_b64_e32 v[28:29], v[12:13]
	v_mov_b64_e32 v[26:27], v[10:11]
	v_mov_b64_e32 v[24:25], v[8:9]
	v_mov_b64_e32 v[22:23], v[6:7]
	v_mov_b64_e32 v[20:21], v[4:5]
	v_mov_b64_e32 v[18:19], v[2:3]
	v_mov_b64_e32 v[16:17], v[0:1]
	v_mov_b64_e32 v[44:45], v[12:13]
	v_mov_b64_e32 v[42:43], v[10:11]
	v_mov_b64_e32 v[40:41], v[8:9]
	v_mov_b64_e32 v[38:39], v[6:7]
	v_mov_b64_e32 v[36:37], v[4:5]
	v_mov_b64_e32 v[34:35], v[2:3]
	v_mov_b64_e32 v[32:33], v[0:1]
	v_mov_b64_e32 v[60:61], v[12:13]
	v_mov_b64_e32 v[58:59], v[10:11]
	v_mov_b64_e32 v[56:57], v[8:9]
	v_mov_b64_e32 v[54:55], v[6:7]
	v_mov_b64_e32 v[52:53], v[4:5]
	v_mov_b64_e32 v[50:51], v[2:3]
	v_mov_b64_e32 v[48:49], v[0:1]
	v_mov_b64_e32 v[76:77], v[12:13]
	v_mov_b64_e32 v[74:75], v[10:11]
	v_mov_b64_e32 v[72:73], v[8:9]
	v_mov_b64_e32 v[70:71], v[6:7]
	v_mov_b64_e32 v[68:69], v[4:5]
	v_mov_b64_e32 v[66:67], v[2:3]
	v_mov_b64_e32 v[64:65], v[0:1]
	v_mov_b32_e32 v2, v203
	v_mov_b32_e32 v3, v196
	v_and_b32_e32 v185, 64, v205
	v_add_u32_e32 v185, 64, v185
	v_xor_b32_e32 v204, 32, v205
	v_cmp_lt_i32_e32 vcc, v204, v185
	v_bfe_u32 v214, v163, 5, 1
	v_and_b32_e32 v15, 31, v163
	v_cndmask_b32_e32 v204, v205, v204, vcc
	v_lshlrev_b32_e32 v185, 2, v204
	v_lshlrev_b32_e32 v12, 4, v214
	v_lshl_add_u32 v13, v214, 3, 16
	v_mul_u32_u24_e32 v204, 0x110, v15
	v_mul_u32_u24_e32 v15, 0x88, v15
	v_add3_u32 v12, v220, v12, v204
	v_lshrrev_b32_e32 v14, 3, v163
	v_add_u32_e32 v13, v13, v15
	v_mul_u32_u24_e32 v14, 0x88, v14
	v_add_u32_e32 v14, v14, v184
; #define MFMA(a, b, c) __builtin_amdgcn_mfma_f32_32x32x16_bf16((a), (b), (c), 0, 0, 0)
; DI float fexp2(float x) { return __builtin_amdgcn_exp2f(x); }
; DI f32x16 zero16() { f32x16 z; for (int i = 0; i < 16; ++i) z[i] = 0.f; return z; }
; template <int DQK, int QR>
; DI void attn_tile64(AttnState<DQK>& st, const bf16x8 (&q)[QR], const u16* Ks, int kcol0, const u16* Vs) {
;     ...
;   f32x16 s[2];
; #pragma unroll
;   for (int kb = 0; kb < 2; ++kb) {
;     s[kb] = zero16();
; #pragma unroll
;     for (int ks = 0; ks < DQK / 16; ++ks) {
;       bf16x8 a = *(const bf16x8*)(Ks + (kb * 32 + r) * KL + kcol0 + ks * 16 + h * 8);
;       s[kb] = MFMA(a, q[ks], s[kb]);
;     }
;   }
;   float mx = s[0][0];
; #pragma unroll
;   for (int kb = 0; kb < 2; ++kb)
; #pragma unroll
;     for (int t = 0; t < 16; ++t) mx = fmaxf(mx, s[kb][t]);
;   mx = fmaxf(mx, __shfl_xor(mx, 32));
;   const float mnew = fmaxf(st.m, mx);
;   const float alpha = fexp2(st.m - mnew);
;   st.m = mnew;
;   float ps = 0.f;
; #pragma unroll
;   for (int kb = 0; kb < 2; ++kb)
; #pragma unroll
;     for (int t = 0; t < 16; ++t) { float pv = fexp2(s[kb][t] - mnew); s[kb][t] = pv; ps += pv; }
;   st.l = st.l * alpha + ps;
;   if (__builtin_amdgcn_ballot_w64(alpha != 1.f) != 0) {
; #pragma unroll
;     for (int eb = 0; eb < 4; ++eb)
; #pragma unroll
;       for (int t = 0; t < 16; ++t) st.ot[eb][t] *= alpha;
;   }
;     ...
;       for (int k0 = 0; k0 < nk; k0 += 64) {
;         __syncthreads();
; #pragma unroll
;         for (int i = 0; i < 4; ++i) { int c = tid + 256 * i, key = c >> 4, kc = c & 15; *(U4*)(Ks + key * KL + kc * 8) = rk[i]; }
; #pragma unroll
;         for (int i = 0; i < 4; ++i) { int c = tid + 256 * i, e = c >> 3, kc = c & 7; *(U4*)(Vs + e * 72 + kc * 8) = rv[i]; }
;         __syncthreads();
;         if (k0 + 64 < nk) gl(k0 + 64);
;         attn_tile64<64, 4>(st, q, Ks, comp * 64, Vs);
.Lda_loop:
	s_add_i32 s20, s70, 64
	s_barrier
	s_waitcnt vmcnt(6)
	ds_write_b128 v191, v[112:115]
	ds_write_b128 v237, v[116:119]
	s_waitcnt vmcnt(4)
	ds_write_b128 v238, v[120:123]
	ds_write_b128 v239, v[124:127]
	s_waitcnt vmcnt(2)
	ds_write_b64 v14, v[128:129] offset:17408
	ds_write_b64 v14, v[130:131] offset:17416
	ds_write_b64 v14, v[132:133] offset:21760
	ds_write_b64 v14, v[134:135] offset:21768
	s_cmp_ge_u32 s20, s19
	s_cselect_b64 s[56:57], -1, 0
	s_waitcnt vmcnt(0)
	ds_write_b64 v14, v[144:145] offset:26112
	ds_write_b64 v14, v[146:147] offset:26120
	ds_write_b64 v14, v[148:149] offset:30464
	ds_write_b64 v14, v[150:151] offset:30472
	s_and_b64 vcc, exec, s[56:57]
	s_waitcnt lgkmcnt(0)
	s_barrier
	ds_read_b128 v[80:83], v12
	ds_read_b128 v[84:87], v12 offset:32
	ds_read_b128 v[88:91], v12 offset:64
	ds_read_b128 v[92:95], v12 offset:96
	ds_read_b128 v[4:7], v12 offset:8704
	ds_read_b128 v[8:11], v12 offset:8736
	ds_read_b128 v[196:199], v12 offset:8768
	ds_read_b128 v[200:203], v12 offset:8800
	s_cbranch_vccnz .Lda_nopf
	v_add_u32_e32 v0, 0xffffa000, v3
	v_lshl_add_u64 v[208:209], v[0:1], 1, s[42:43]
	global_load_dwordx4 v[112:115], v[208:209], off
	v_add_u32_e32 v0, 0xffffc000, v3
	v_lshl_add_u64 v[210:211], v[0:1], 1, s[42:43]
	global_load_dwordx4 v[116:119], v[210:211], off
	v_add_u32_e32 v0, 0xffffe000, v3
	v_lshl_add_u64 v[208:209], v[0:1], 1, s[42:43]
	global_load_dwordx4 v[120:123], v[208:209], off
	v_mov_b32_e32 v0, v3
	v_lshl_add_u64 v[210:211], v[0:1], 1, s[42:43]
	global_load_dwordx4 v[124:127], v[210:211], off
	v_add_u32_e32 v214, s70, v170
	v_add_u32_e32 v0, 64, v214
	v_lshl_add_u64 v[208:209], v[0:1], 1, s[44:45]
	global_load_dwordx4 v[128:131], v[208:209], off
	v_add_u32_e32 v0, 0x42040, v214
	v_lshl_add_u64 v[210:211], v[0:1], 1, s[44:45]
	global_load_dwordx4 v[132:135], v[210:211], off
	v_add_u32_e32 v0, 0x84040, v214
	v_lshl_add_u64 v[208:209], v[0:1], 1, s[44:45]
	global_load_dwordx4 v[144:147], v[208:209], off
	v_add_u32_e32 v0, 0xc6040, v214
	v_lshl_add_u64 v[210:211], v[0:1], 1, s[44:45]
	global_load_dwordx4 v[148:151], v[210:211], off
	v_add_u32_e32 v3, 0x8000, v3
.Lda_nopf:
	s_waitcnt lgkmcnt(7)
	v_mfma_f32_32x32x16_bf16 v[96:111], v[80:83], v[136:139], 0
	s_waitcnt lgkmcnt(6)
	v_mfma_f32_32x32x16_bf16 v[96:111], v[84:87], v[140:143], v[96:111]
	s_waitcnt lgkmcnt(5)
	v_mfma_f32_32x32x16_bf16 v[96:111], v[88:91], v[152:155], v[96:111]
	s_waitcnt lgkmcnt(4)
	v_mfma_f32_32x32x16_bf16 v[96:111], v[92:95], v[156:159], v[96:111]
	s_waitcnt lgkmcnt(3)
	v_mfma_f32_32x32x16_bf16 v[80:95], v[4:7], v[136:139], 0
	ds_read_b64 v[4:5], v13 offset:17408
	ds_read_b64 v[6:7], v13 offset:17424
	s_waitcnt lgkmcnt(4)
	v_mfma_f32_32x32x16_bf16 v[80:95], v[8:11], v[140:143], v[80:95]
	ds_read_b64 v[8:9], v13 offset:21760
	ds_read_b64 v[10:11], v13 offset:21776
	s_waitcnt lgkmcnt(5)
	v_mfma_f32_32x32x16_bf16 v[80:95], v[196:199], v[152:155], v[80:95]
	ds_read_b64 v[196:197], v13 offset:26112
	ds_read_b64 v[198:199], v13 offset:26128
	s_waitcnt lgkmcnt(6)
	v_mfma_f32_32x32x16_bf16 v[80:95], v[200:203], v[156:159], v[80:95]
	ds_read_b64 v[200:201], v13 offset:30464
	ds_read_b64 v[202:203], v13 offset:30480
	v_max3_f32 v204, v96, v97, v98
	v_max3_f32 v204, v204, v99, v100
	v_max3_f32 v204, v204, v101, v102
	v_max3_f32 v204, v204, v103, v104
	v_max3_f32 v204, v204, v105, v106
	v_max3_f32 v204, v204, v107, v108
	v_max3_f32 v204, v204, v109, v110
	v_max_f32_e32 v204, v204, v111
	s_nop 2
	v_max3_f32 v214, v80, v81, v82
	v_max3_f32 v214, v214, v83, v84
	v_max3_f32 v214, v214, v85, v86
	v_max3_f32 v214, v214, v87, v88
	v_max3_f32 v214, v214, v89, v90
	v_max3_f32 v214, v214, v91, v92
	v_max3_f32 v214, v214, v93, v94
	v_max3_f32 v204, v204, v214, v95
	ds_bpermute_b32 v214, v185, v204
	s_waitcnt lgkmcnt(0)
	v_max3_f32 v204, v2, v204, v214
	v_sub_f32_e32 v0, v2, v204
	v_exp_f32_e32 v0, v0
	v_mov_b32_e32 v2, v204
	v_cmp_neq_f32_e32 vcc, 1.0, v0
	s_cbranch_vccz .Lda_norescale
	v_pk_mul_f32 v[78:79], v[78:79], v[0:1] op_sel_hi:[1,0]
	v_pk_mul_f32 v[76:77], v[76:77], v[0:1] op_sel_hi:[1,0]
	v_pk_mul_f32 v[74:75], v[74:75], v[0:1] op_sel_hi:[1,0]
	v_pk_mul_f32 v[72:73], v[72:73], v[0:1] op_sel_hi:[1,0]
	v_pk_mul_f32 v[70:71], v[70:71], v[0:1] op_sel_hi:[1,0]
	v_pk_mul_f32 v[68:69], v[68:69], v[0:1] op_sel_hi:[1,0]
	v_pk_mul_f32 v[66:67], v[66:67], v[0:1] op_sel_hi:[1,0]
	v_pk_mul_f32 v[64:65], v[64:65], v[0:1] op_sel_hi:[1,0]
	v_pk_mul_f32 v[62:63], v[62:63], v[0:1] op_sel_hi:[1,0]
	v_pk_mul_f32 v[60:61], v[60:61], v[0:1] op_sel_hi:[1,0]
	v_pk_mul_f32 v[58:59], v[58:59], v[0:1] op_sel_hi:[1,0]
	v_pk_mul_f32 v[56:57], v[56:57], v[0:1] op_sel_hi:[1,0]
	v_pk_mul_f32 v[54:55], v[54:55], v[0:1] op_sel_hi:[1,0]
	v_pk_mul_f32 v[52:53], v[52:53], v[0:1] op_sel_hi:[1,0]
	v_pk_mul_f32 v[50:51], v[50:51], v[0:1] op_sel_hi:[1,0]
	v_pk_mul_f32 v[48:49], v[48:49], v[0:1] op_sel_hi:[1,0]
	v_pk_mul_f32 v[46:47], v[46:47], v[0:1] op_sel_hi:[1,0]
	v_pk_mul_f32 v[44:45], v[44:45], v[0:1] op_sel_hi:[1,0]
	v_pk_mul_f32 v[42:43], v[42:43], v[0:1] op_sel_hi:[1,0]
	v_pk_mul_f32 v[40:41], v[40:41], v[0:1] op_sel_hi:[1,0]
	v_pk_mul_f32 v[38:39], v[38:39], v[0:1] op_sel_hi:[1,0]
	v_pk_mul_f32 v[36:37], v[36:37], v[0:1] op_sel_hi:[1,0]
	v_pk_mul_f32 v[34:35], v[34:35], v[0:1] op_sel_hi:[1,0]
	v_pk_mul_f32 v[32:33], v[32:33], v[0:1] op_sel_hi:[1,0]
	v_pk_mul_f32 v[30:31], v[30:31], v[0:1] op_sel_hi:[1,0]
	v_pk_mul_f32 v[28:29], v[28:29], v[0:1] op_sel_hi:[1,0]
	v_pk_mul_f32 v[26:27], v[26:27], v[0:1] op_sel_hi:[1,0]
	v_pk_mul_f32 v[24:25], v[24:25], v[0:1] op_sel_hi:[1,0]
	v_pk_mul_f32 v[22:23], v[22:23], v[0:1] op_sel_hi:[1,0]
	v_pk_mul_f32 v[20:21], v[20:21], v[0:1] op_sel_hi:[1,0]
	v_pk_mul_f32 v[18:19], v[18:19], v[0:1] op_sel_hi:[1,0]
	v_pk_mul_f32 v[16:17], v[16:17], v[0:1] op_sel_hi:[1,0]
; #define MFMA(a, b, c) __builtin_amdgcn_mfma_f32_32x32x16_bf16((a), (b), (c), 0, 0, 0)
; DI unsigned pack2(float a, float b) { F2 v = {a, b}; B2 r = __builtin_convertvector(v, B2); return __builtin_bit_cast(unsigned, r); }
; DI float fexp2(float x) { return __builtin_amdgcn_exp2f(x); }
; template <int DQK, int QR>
; DI void attn_tile64(AttnState<DQK>& st, const bf16x8 (&q)[QR], const u16* Ks, int kcol0, const u16* Vs) {
;     ...
;   float ps = 0.f;
; #pragma unroll
;   for (int kb = 0; kb < 2; ++kb)
; #pragma unroll
;     for (int t = 0; t < 16; ++t) { float pv = fexp2(s[kb][t] - mnew); s[kb][t] = pv; ps += pv; }
;   st.l = st.l * alpha + ps;
;   if (__builtin_amdgcn_ballot_w64(alpha != 1.f) != 0) {
; #pragma unroll
;     for (int eb = 0; eb < 4; ++eb)
; #pragma unroll
;       for (int t = 0; t < 16; ++t) st.ot[eb][t] *= alpha;
;   }
; #pragma unroll
;   for (int kb = 0; kb < 2; ++kb)
; #pragma unroll
;     for (int s2 = 0; s2 < 2; ++s2) {
;       unsigned pk[4];
; #pragma unroll
;       for (int j = 0; j < 4; ++j) pk[j] = pack2(s[kb][8 * s2 + 2 * j], s[kb][8 * s2 + 2 * j + 1]);
;       bf16x8 pf = __builtin_bit_cast(bf16x8, mku4(pk[0], pk[1], pk[2], pk[3]));
; #pragma unroll
;       for (int eb = 0; eb < 4; ++eb) {
;         const u16* vp = Vs + (eb * 32 + r) * 72 + kb * 32 + 16 * s2 + 4 * h;
;         U2 lo = *(const U2*)vp, hi = *(const U2*)(vp + 8);
;         bf16x8 vf = __builtin_bit_cast(bf16x8, mku4(lo.x, lo.y, hi.x, hi.y));
;         st.ot[eb] = MFMA(vf, pf, st.ot[eb]);
;       }
;     }
.Lda_norescale:
	v_sub_f32_e32 v96, v96, v204
	v_exp_f32_e32 v96, v96
	v_sub_f32_e32 v97, v97, v204
	v_exp_f32_e32 v97, v97
	v_add_f32_e32 v15, 0, v96
	v_sub_f32_e32 v98, v98, v204
	v_exp_f32_e32 v98, v98
	v_add_f32_e32 v15, v97, v15
	v_sub_f32_e32 v99, v99, v204
	v_exp_f32_e32 v99, v99
	v_add_f32_e32 v15, v98, v15
	v_sub_f32_e32 v100, v100, v204
	v_exp_f32_e32 v100, v100
	v_add_f32_e32 v15, v99, v15
	v_sub_f32_e32 v101, v101, v204
	v_exp_f32_e32 v101, v101
	v_add_f32_e32 v15, v100, v15
	v_sub_f32_e32 v102, v102, v204
	v_exp_f32_e32 v102, v102
	v_add_f32_e32 v15, v101, v15
	v_sub_f32_e32 v103, v103, v204
	v_exp_f32_e32 v103, v103
	v_add_f32_e32 v15, v102, v15
	v_sub_f32_e32 v104, v104, v204
	v_exp_f32_e32 v104, v104
	v_add_f32_e32 v15, v103, v15
	v_sub_f32_e32 v105, v105, v204
	v_exp_f32_e32 v105, v105
	v_add_f32_e32 v15, v104, v15
	v_sub_f32_e32 v106, v106, v204
	v_exp_f32_e32 v106, v106
	v_add_f32_e32 v15, v105, v15
	v_sub_f32_e32 v107, v107, v204
	v_exp_f32_e32 v107, v107
	v_add_f32_e32 v15, v106, v15
	v_sub_f32_e32 v108, v108, v204
	v_exp_f32_e32 v108, v108
	v_add_f32_e32 v15, v107, v15
	v_sub_f32_e32 v109, v109, v204
	v_exp_f32_e32 v109, v109
	v_add_f32_e32 v15, v108, v15
	v_sub_f32_e32 v110, v110, v204
	v_exp_f32_e32 v110, v110
	v_add_f32_e32 v15, v109, v15
	v_sub_f32_e32 v111, v111, v204
	v_exp_f32_e32 v111, v111
	v_add_f32_e32 v15, v110, v15
	v_sub_f32_e32 v80, v80, v204
	v_exp_f32_e32 v80, v80
	v_add_f32_e32 v15, v111, v15
	v_sub_f32_e32 v81, v81, v204
	v_exp_f32_e32 v81, v81
	v_add_f32_e32 v15, v80, v15
	v_sub_f32_e32 v82, v82, v204
	v_exp_f32_e32 v82, v82
	v_add_f32_e32 v15, v81, v15
	v_sub_f32_e32 v83, v83, v204
	v_exp_f32_e32 v83, v83
	v_add_f32_e32 v15, v82, v15
	v_sub_f32_e32 v84, v84, v204
	v_exp_f32_e32 v84, v84
	v_add_f32_e32 v15, v83, v15
	v_sub_f32_e32 v85, v85, v204
	v_exp_f32_e32 v85, v85
	v_add_f32_e32 v15, v84, v15
	v_sub_f32_e32 v86, v86, v204
	v_exp_f32_e32 v86, v86
	v_add_f32_e32 v15, v85, v15
	v_sub_f32_e32 v87, v87, v204
	v_exp_f32_e32 v87, v87
	v_add_f32_e32 v15, v86, v15
	v_sub_f32_e32 v88, v88, v204
	v_exp_f32_e32 v88, v88
	v_add_f32_e32 v15, v87, v15
	v_sub_f32_e32 v89, v89, v204
	v_exp_f32_e32 v89, v89
	v_add_f32_e32 v15, v88, v15
	v_sub_f32_e32 v90, v90, v204
	v_exp_f32_e32 v90, v90
	v_add_f32_e32 v15, v89, v15
	v_sub_f32_e32 v91, v91, v204
	v_exp_f32_e32 v91, v91
	v_add_f32_e32 v15, v90, v15
	v_sub_f32_e32 v92, v92, v204
	v_exp_f32_e32 v92, v92
	v_add_f32_e32 v15, v91, v15
	v_sub_f32_e32 v93, v93, v204
	v_exp_f32_e32 v93, v93
	v_add_f32_e32 v15, v92, v15
	v_sub_f32_e32 v94, v94, v204
	v_exp_f32_e32 v94, v94
	v_add_f32_e32 v15, v93, v15
	v_sub_f32_e32 v95, v95, v204
	v_exp_f32_e32 v95, v95
	v_add_f32_e32 v15, v94, v15
	s_nop 0
	v_add_f32_e32 v15, v95, v15
	v_fmac_f32_e32 v15, v193, v0
	v_cvt_pk_bf16_f32 v96, v96, v97
	v_cvt_pk_bf16_f32 v97, v98, v99
	v_cvt_pk_bf16_f32 v98, v100, v101
	v_cvt_pk_bf16_f32 v99, v102, v103
	v_cvt_pk_bf16_f32 v104, v104, v105
	v_cvt_pk_bf16_f32 v105, v106, v107
	v_cvt_pk_bf16_f32 v106, v108, v109
	v_cvt_pk_bf16_f32 v107, v110, v111
	v_cvt_pk_bf16_f32 v80, v80, v81
	v_cvt_pk_bf16_f32 v81, v82, v83
	v_cvt_pk_bf16_f32 v82, v84, v85
	v_cvt_pk_bf16_f32 v83, v86, v87
	v_cvt_pk_bf16_f32 v88, v88, v89
	v_cvt_pk_bf16_f32 v89, v90, v91
	v_cvt_pk_bf16_f32 v90, v92, v93
	v_cvt_pk_bf16_f32 v91, v94, v95
	v_mov_b32_e32 v193, v15
	ds_read_b64 v[100:101], v13 offset:17440
	ds_read_b64 v[102:103], v13 offset:17456
	ds_read_b64 v[108:109], v13 offset:21792
	ds_read_b64 v[110:111], v13 offset:21808
	ds_read_b64 v[84:85], v13 offset:26144
	ds_read_b64 v[86:87], v13 offset:26160
	ds_read_b64 v[92:93], v13 offset:30496
	ds_read_b64 v[94:95], v13 offset:30512
	s_waitcnt lgkmcnt(15)
	v_mfma_f32_32x32x16_bf16 v[64:79], v[4:7], v[96:99], v[64:79]
	s_waitcnt lgkmcnt(13)
	v_mfma_f32_32x32x16_bf16 v[48:63], v[8:11], v[96:99], v[48:63]
	s_waitcnt lgkmcnt(11)
	v_mfma_f32_32x32x16_bf16 v[32:47], v[196:199], v[96:99], v[32:47]
	s_waitcnt lgkmcnt(9)
	v_mfma_f32_32x32x16_bf16 v[16:31], v[200:203], v[96:99], v[16:31]
	s_waitcnt lgkmcnt(6)
	v_mfma_f32_32x32x16_bf16 v[64:79], v[100:103], v[104:107], v[64:79]
	ds_read_b64 v[100:101], v13 offset:17472
	ds_read_b64 v[102:103], v13 offset:17488
	s_waitcnt lgkmcnt(6)
	v_mfma_f32_32x32x16_bf16 v[48:63], v[108:111], v[104:107], v[48:63]
	ds_read_b64 v[108:109], v13 offset:21824
	ds_read_b64 v[110:111], v13 offset:21840
	s_waitcnt lgkmcnt(6)
	v_mfma_f32_32x32x16_bf16 v[32:47], v[84:87], v[104:107], v[32:47]
	ds_read_b64 v[84:85], v13 offset:26176
	ds_read_b64 v[86:87], v13 offset:26192
	s_waitcnt lgkmcnt(6)
	v_mfma_f32_32x32x16_bf16 v[16:31], v[92:95], v[104:107], v[16:31]
	ds_read_b64 v[92:93], v13 offset:30528
	ds_read_b64 v[94:95], v13 offset:30544
	s_waitcnt lgkmcnt(6)
	v_mfma_f32_32x32x16_bf16 v[64:79], v[100:103], v[80:83], v[64:79]
	ds_read_b64 v[100:101], v13 offset:17504
	ds_read_b64 v[102:103], v13 offset:17520
	s_waitcnt lgkmcnt(6)
	v_mfma_f32_32x32x16_bf16 v[48:63], v[108:111], v[80:83], v[48:63]
	ds_read_b64 v[108:109], v13 offset:21856
	ds_read_b64 v[110:111], v13 offset:21872
	s_waitcnt lgkmcnt(6)
	v_mfma_f32_32x32x16_bf16 v[32:47], v[84:87], v[80:83], v[32:47]
	ds_read_b64 v[84:85], v13 offset:26208
	ds_read_b64 v[86:87], v13 offset:26224
	s_waitcnt lgkmcnt(6)
	v_mfma_f32_32x32x16_bf16 v[16:31], v[92:95], v[80:83], v[16:31]
	ds_read_b64 v[92:93], v13 offset:30560
	ds_read_b64 v[94:95], v13 offset:30576
	s_waitcnt lgkmcnt(6)
	v_mfma_f32_32x32x16_bf16 v[64:79], v[100:103], v[88:91], v[64:79]
	s_waitcnt lgkmcnt(4)
	v_mfma_f32_32x32x16_bf16 v[48:63], v[108:111], v[88:91], v[48:63]
	s_waitcnt lgkmcnt(2)
	v_mfma_f32_32x32x16_bf16 v[32:47], v[84:87], v[88:91], v[32:47]
	s_waitcnt lgkmcnt(0)
	v_mfma_f32_32x32x16_bf16 v[16:31], v[92:95], v[88:91], v[16:31]
	s_and_b64 vcc, exec, s[56:57]
	s_mov_b32 s70, s20
	s_cbranch_vccz .Lda_loop
	v_mov_b32_e32 v3, v193
	s_branch .LBB0_687
